# v68 + hand-written out-projection epilogue for prompt tiles (batched loads)
# baseline (speedup 1.0000x reference)
.LBB0_1055:
	s_and_b64 vcc, exec, s[6:7]
	s_cbranch_vccz .LBB0_991
	s_cmp_eq_u64 s[0:1], 0
	s_cbranch_scc0 .Leo_nonext
	s_ashr_i32 s6, s37, 3
	s_mul_i32 s6, s6, 0xc000
	s_add_u32 s6, s46, s6
	s_addc_u32 s7, s47, 0
	s_add_i32 s8, s8, s29
	v_add_u32_e32 v251, s8, v207
	v_lshlrev_b32_e32 v250, 11, v251
	v_lshl_add_u32 v250, v168, 1, v250
	v_lshlrev_b32_e32 v251, 2, v251
	v_lshlrev_b32_e32 v242, 2, v168
	v_add_u32_e32 v243, 0x2000, v242
	v_add_u32_e32 v244, 0x4000, v242
	global_load_dwordx4 v[130:133], v243, s[6:7] offset:0
	global_load_dwordx4 v[134:137], v243, s[6:7] offset:16
	global_load_dwordx4 v[138:141], v243, s[6:7] offset:512
	global_load_dwordx4 v[142:145], v243, s[6:7] offset:528
	global_load_dwordx4 v[170:173], v244, s[6:7] offset:0
	global_load_dwordx4 v[174:177], v244, s[6:7] offset:16
	global_load_dwordx4 v[178:181], v244, s[6:7] offset:512
	global_load_dwordx4 v[182:185], v244, s[6:7] offset:528
	global_load_dwordx4 v[186:189], v242, s[48:49] offset:0
	global_load_dwordx4 v[190:193], v242, s[48:49] offset:16
	global_load_dwordx4 v[194:197], v242, s[48:49] offset:512
	global_load_dwordx4 v[198:201], v242, s[48:49] offset:528
	v_xor_b32_e32 v219, 16, v233
	v_lshlrev_b32_e32 v219, 2, v219
	v_xor_b32_e32 v241, 32, v233
	v_lshlrev_b32_e32 v241, 2, v241
	v_cmp_eq_u32_e64 s[98:99], 0, v217
	s_add_u32 s6, s94, 0x10000
	s_addc_u32 s7, s95, 0
	global_load_dwordx4 v[146:149], v250, s[6:7] offset:0
	global_load_dwordx4 v[150:153], v250, s[6:7] offset:256
	s_add_u32 s6, s94, 0x18000
	s_addc_u32 s7, s95, 0
	global_load_dwordx4 v[154:157], v250, s[6:7] offset:0
	global_load_dwordx4 v[210:213], v250, s[6:7] offset:256
	s_waitcnt vmcnt(4)
	v_pk_add_f32 v[130:131], v[130:131], 1.0 op_sel_hi:[1,0]
	v_pk_add_f32 v[132:133], v[132:133], 1.0 op_sel_hi:[1,0]
	v_pk_add_f32 v[134:135], v[134:135], 1.0 op_sel_hi:[1,0]
	v_pk_add_f32 v[136:137], v[136:137], 1.0 op_sel_hi:[1,0]
	v_pk_add_f32 v[138:139], v[138:139], 1.0 op_sel_hi:[1,0]
	v_pk_add_f32 v[140:141], v[140:141], 1.0 op_sel_hi:[1,0]
	v_pk_add_f32 v[142:143], v[142:143], 1.0 op_sel_hi:[1,0]
	v_pk_add_f32 v[144:145], v[144:145], 1.0 op_sel_hi:[1,0]
	v_pk_add_f32 v[170:171], v[170:171], 1.0 op_sel_hi:[1,0]
	v_pk_add_f32 v[172:173], v[172:173], 1.0 op_sel_hi:[1,0]
	v_pk_add_f32 v[174:175], v[174:175], 1.0 op_sel_hi:[1,0]
	v_pk_add_f32 v[176:177], v[176:177], 1.0 op_sel_hi:[1,0]
	v_pk_add_f32 v[178:179], v[178:179], 1.0 op_sel_hi:[1,0]
	v_pk_add_f32 v[180:181], v[180:181], 1.0 op_sel_hi:[1,0]
	v_pk_add_f32 v[182:183], v[182:183], 1.0 op_sel_hi:[1,0]
	v_pk_add_f32 v[184:185], v[184:185], 1.0 op_sel_hi:[1,0]
	v_pk_mul_f32 v[170:171], v[170:171], v[186:187]
	v_pk_mul_f32 v[172:173], v[172:173], v[188:189]
	v_pk_mul_f32 v[174:175], v[174:175], v[190:191]
	v_pk_mul_f32 v[176:177], v[176:177], v[192:193]
	v_pk_mul_f32 v[178:179], v[178:179], v[194:195]
	v_pk_mul_f32 v[180:181], v[180:181], v[196:197]
	v_pk_mul_f32 v[182:183], v[182:183], v[198:199]
	v_pk_mul_f32 v[184:185], v[184:185], v[200:201]
	s_add_u32 s6, s94, 0x0
	s_addc_u32 s7, s95, 0
	global_load_dwordx4 v[186:189], v250, s[6:7] offset:0
	global_load_dwordx4 v[190:193], v250, s[6:7] offset:256
	s_add_u32 s6, s94, 0x8000
	s_addc_u32 s7, s95, 0
	global_load_dwordx4 v[194:197], v250, s[6:7] offset:0
	global_load_dwordx4 v[198:201], v250, s[6:7] offset:256
	s_waitcnt vmcnt(3)
	v_lshlrev_b32_e32 v242, 16, v186
	v_and_b32_e32 v243, 0xffff0000, v186
	v_lshlrev_b32_e32 v244, 16, v187
	v_and_b32_e32 v245, 0xffff0000, v187
	v_lshlrev_b32_e32 v246, 16, v188
	v_and_b32_e32 v247, 0xffff0000, v188
	v_lshlrev_b32_e32 v248, 16, v189
	v_and_b32_e32 v249, 0xffff0000, v189
	v_pk_fma_f32 v[126:127], v[126:127], v[130:131], v[242:243]
	v_pk_fma_f32 v[128:129], v[128:129], v[132:133], v[244:245]
	v_pk_fma_f32 v[122:123], v[122:123], v[134:135], v[246:247]
	v_pk_fma_f32 v[124:125], v[124:125], v[136:137], v[248:249]
	v_cvt_pk_bf16_f32 v186, v126, v127
	v_cvt_pk_bf16_f32 v187, v128, v129
	v_cvt_pk_bf16_f32 v188, v122, v123
	v_cvt_pk_bf16_f32 v189, v124, v125
	s_add_u32 s6, s94, 0x0
	s_addc_u32 s7, s95, 0
	global_store_dwordx4 v250, v[186:189], s[6:7] offset:0
	v_pk_mul_f32 v[242:243], v[126:127], v[126:127]
	v_pk_fma_f32 v[242:243], v[128:129], v[128:129], v[242:243]
	v_pk_fma_f32 v[242:243], v[122:123], v[122:123], v[242:243]
	v_pk_fma_f32 v[242:243], v[124:125], v[124:125], v[242:243]
	v_add_f32_e32 v218, v242, v243
	v_pk_mul_f32 v[126:127], v[126:127], v[170:171]
	v_pk_mul_f32 v[128:129], v[128:129], v[172:173]
	v_pk_mul_f32 v[122:123], v[122:123], v[174:175]
	v_pk_mul_f32 v[124:125], v[124:125], v[176:177]
	v_cvt_pk_bf16_f32 v186, v126, v127
	v_cvt_pk_bf16_f32 v187, v128, v129
	v_cvt_pk_bf16_f32 v188, v122, v123
	v_cvt_pk_bf16_f32 v189, v124, v125
	s_add_u32 s40, s72, 0x0
	s_addc_u32 s41, s73, 0
	global_store_dwordx4 v250, v[186:189], s[40:41] offset:0
	s_nop 1
	s_add_u32 s6, s94, 0x40000
	s_addc_u32 s7, s95, 0
	global_load_dwordx4 v[186:189], v250, s[6:7] offset:0
	s_waitcnt vmcnt(5)
	v_lshlrev_b32_e32 v242, 16, v190
	v_and_b32_e32 v243, 0xffff0000, v190
	v_lshlrev_b32_e32 v244, 16, v191
	v_and_b32_e32 v245, 0xffff0000, v191
	v_lshlrev_b32_e32 v246, 16, v192
	v_and_b32_e32 v247, 0xffff0000, v192
	v_lshlrev_b32_e32 v248, 16, v193
	v_and_b32_e32 v249, 0xffff0000, v193
	v_pk_fma_f32 v[118:119], v[118:119], v[138:139], v[242:243]
	v_pk_fma_f32 v[120:121], v[120:121], v[140:141], v[244:245]
	v_pk_fma_f32 v[114:115], v[114:115], v[142:143], v[246:247]
	v_pk_fma_f32 v[116:117], v[116:117], v[144:145], v[248:249]
	v_cvt_pk_bf16_f32 v190, v118, v119
	v_cvt_pk_bf16_f32 v191, v120, v121
	v_cvt_pk_bf16_f32 v192, v114, v115
	v_cvt_pk_bf16_f32 v193, v116, v117
	s_add_u32 s6, s94, 0x0
	s_addc_u32 s7, s95, 0
	global_store_dwordx4 v250, v[190:193], s[6:7] offset:256
	v_pk_mul_f32 v[242:243], v[118:119], v[118:119]
	v_pk_fma_f32 v[242:243], v[120:121], v[120:121], v[242:243]
	v_pk_fma_f32 v[242:243], v[114:115], v[114:115], v[242:243]
	v_pk_fma_f32 v[242:243], v[116:117], v[116:117], v[242:243]
	v_add_f32_e32 v242, v242, v243
	v_add_f32_e32 v218, v218, v242
	v_pk_mul_f32 v[118:119], v[118:119], v[178:179]
	v_pk_mul_f32 v[120:121], v[120:121], v[180:181]
	v_pk_mul_f32 v[114:115], v[114:115], v[182:183]
	v_pk_mul_f32 v[116:117], v[116:117], v[184:185]
	v_cvt_pk_bf16_f32 v190, v118, v119
	v_cvt_pk_bf16_f32 v191, v120, v121
	v_cvt_pk_bf16_f32 v192, v114, v115
	v_cvt_pk_bf16_f32 v193, v116, v117
	s_add_u32 s40, s72, 0x0
	s_addc_u32 s41, s73, 0
	global_store_dwordx4 v250, v[190:193], s[40:41] offset:256
	s_nop 1
	s_add_u32 s6, s94, 0x40000
	s_addc_u32 s7, s95, 0
	global_load_dwordx4 v[190:193], v250, s[6:7] offset:256
	ds_bpermute_b32 v242, v219, v218
	s_waitcnt lgkmcnt(0)
	v_add_f32_e32 v218, v218, v242
	ds_bpermute_b32 v242, v241, v218
	s_waitcnt lgkmcnt(0)
	v_add_f32_e32 v218, v218, v242
	s_add_u32 s100, s50, 0x0
	s_addc_u32 s101, s51, 0
	s_and_saveexec_b64 s[40:41], s[98:99]
	global_atomic_add_f32 v251, v218, s[100:101]
	s_or_b64 exec, exec, s[40:41]
	s_waitcnt vmcnt(8)
	v_lshlrev_b32_e32 v242, 16, v194
	v_and_b32_e32 v243, 0xffff0000, v194
	v_lshlrev_b32_e32 v244, 16, v195
	v_and_b32_e32 v245, 0xffff0000, v195
	v_lshlrev_b32_e32 v246, 16, v196
	v_and_b32_e32 v247, 0xffff0000, v196
	v_lshlrev_b32_e32 v248, 16, v197
	v_and_b32_e32 v249, 0xffff0000, v197
	v_pk_fma_f32 v[110:111], v[110:111], v[130:131], v[242:243]
	v_pk_fma_f32 v[112:113], v[112:113], v[132:133], v[244:245]
	v_pk_fma_f32 v[106:107], v[106:107], v[134:135], v[246:247]
	v_pk_fma_f32 v[108:109], v[108:109], v[136:137], v[248:249]
	v_cvt_pk_bf16_f32 v194, v110, v111
	v_cvt_pk_bf16_f32 v195, v112, v113
	v_cvt_pk_bf16_f32 v196, v106, v107
	v_cvt_pk_bf16_f32 v197, v108, v109
	s_add_u32 s6, s94, 0x8000
	s_addc_u32 s7, s95, 0
	global_store_dwordx4 v250, v[194:197], s[6:7] offset:0
	v_pk_mul_f32 v[242:243], v[110:111], v[110:111]
	v_pk_fma_f32 v[242:243], v[112:113], v[112:113], v[242:243]
	v_pk_fma_f32 v[242:243], v[106:107], v[106:107], v[242:243]
	v_pk_fma_f32 v[242:243], v[108:109], v[108:109], v[242:243]
	v_add_f32_e32 v218, v242, v243
	v_pk_mul_f32 v[110:111], v[110:111], v[170:171]
	v_pk_mul_f32 v[112:113], v[112:113], v[172:173]
	v_pk_mul_f32 v[106:107], v[106:107], v[174:175]
	v_pk_mul_f32 v[108:109], v[108:109], v[176:177]
	v_cvt_pk_bf16_f32 v194, v110, v111
	v_cvt_pk_bf16_f32 v195, v112, v113
	v_cvt_pk_bf16_f32 v196, v106, v107
	v_cvt_pk_bf16_f32 v197, v108, v109
	s_add_u32 s40, s72, 0x8000
	s_addc_u32 s41, s73, 0
	global_store_dwordx4 v250, v[194:197], s[40:41] offset:0
	s_nop 1
	s_add_u32 s6, s94, 0x48000
	s_addc_u32 s7, s95, 0
	global_load_dwordx4 v[194:197], v250, s[6:7] offset:0
	s_waitcnt vmcnt(10)
	v_lshlrev_b32_e32 v242, 16, v198
	v_and_b32_e32 v243, 0xffff0000, v198
	v_lshlrev_b32_e32 v244, 16, v199
	v_and_b32_e32 v245, 0xffff0000, v199
	v_lshlrev_b32_e32 v246, 16, v200
	v_and_b32_e32 v247, 0xffff0000, v200
	v_lshlrev_b32_e32 v248, 16, v201
	v_and_b32_e32 v249, 0xffff0000, v201
	v_pk_fma_f32 v[102:103], v[102:103], v[138:139], v[242:243]
	v_pk_fma_f32 v[104:105], v[104:105], v[140:141], v[244:245]
	v_pk_fma_f32 v[98:99], v[98:99], v[142:143], v[246:247]
	v_pk_fma_f32 v[100:101], v[100:101], v[144:145], v[248:249]
	v_cvt_pk_bf16_f32 v198, v102, v103
	v_cvt_pk_bf16_f32 v199, v104, v105
	v_cvt_pk_bf16_f32 v200, v98, v99
	v_cvt_pk_bf16_f32 v201, v100, v101
	s_add_u32 s6, s94, 0x8000
	s_addc_u32 s7, s95, 0
	global_store_dwordx4 v250, v[198:201], s[6:7] offset:256
	v_pk_mul_f32 v[242:243], v[102:103], v[102:103]
	v_pk_fma_f32 v[242:243], v[104:105], v[104:105], v[242:243]
	v_pk_fma_f32 v[242:243], v[98:99], v[98:99], v[242:243]
	v_pk_fma_f32 v[242:243], v[100:101], v[100:101], v[242:243]
	v_add_f32_e32 v242, v242, v243
	v_add_f32_e32 v218, v218, v242
	v_pk_mul_f32 v[102:103], v[102:103], v[178:179]
	v_pk_mul_f32 v[104:105], v[104:105], v[180:181]
	v_pk_mul_f32 v[98:99], v[98:99], v[182:183]
	v_pk_mul_f32 v[100:101], v[100:101], v[184:185]
	v_cvt_pk_bf16_f32 v198, v102, v103
	v_cvt_pk_bf16_f32 v199, v104, v105
	v_cvt_pk_bf16_f32 v200, v98, v99
	v_cvt_pk_bf16_f32 v201, v100, v101
	s_add_u32 s40, s72, 0x8000
	s_addc_u32 s41, s73, 0
	global_store_dwordx4 v250, v[198:201], s[40:41] offset:256
	s_nop 1
	s_add_u32 s6, s94, 0x48000
	s_addc_u32 s7, s95, 0
	global_load_dwordx4 v[198:201], v250, s[6:7] offset:256
	ds_bpermute_b32 v242, v219, v218
	s_waitcnt lgkmcnt(0)
	v_add_f32_e32 v218, v218, v242
	ds_bpermute_b32 v242, v241, v218
	s_waitcnt lgkmcnt(0)
	v_add_f32_e32 v218, v218, v242
	s_add_u32 s100, s50, 0x40
	s_addc_u32 s101, s51, 0
	s_and_saveexec_b64 s[40:41], s[98:99]
	global_atomic_add_f32 v251, v218, s[100:101]
	s_or_b64 exec, exec, s[40:41]
	v_lshlrev_b32_e32 v242, 16, v146
	v_and_b32_e32 v243, 0xffff0000, v146
	v_lshlrev_b32_e32 v244, 16, v147
	v_and_b32_e32 v245, 0xffff0000, v147
	v_lshlrev_b32_e32 v246, 16, v148
	v_and_b32_e32 v247, 0xffff0000, v148
	v_lshlrev_b32_e32 v248, 16, v149
	v_and_b32_e32 v249, 0xffff0000, v149
	v_pk_fma_f32 v[94:95], v[94:95], v[130:131], v[242:243]
	v_pk_fma_f32 v[96:97], v[96:97], v[132:133], v[244:245]
	v_pk_fma_f32 v[90:91], v[90:91], v[134:135], v[246:247]
	v_pk_fma_f32 v[92:93], v[92:93], v[136:137], v[248:249]
	v_cvt_pk_bf16_f32 v146, v94, v95
	v_cvt_pk_bf16_f32 v147, v96, v97
	v_cvt_pk_bf16_f32 v148, v90, v91
	v_cvt_pk_bf16_f32 v149, v92, v93
	s_add_u32 s6, s94, 0x10000
	s_addc_u32 s7, s95, 0
	global_store_dwordx4 v250, v[146:149], s[6:7] offset:0
	v_pk_mul_f32 v[242:243], v[94:95], v[94:95]
	v_pk_fma_f32 v[242:243], v[96:97], v[96:97], v[242:243]
	v_pk_fma_f32 v[242:243], v[90:91], v[90:91], v[242:243]
	v_pk_fma_f32 v[242:243], v[92:93], v[92:93], v[242:243]
	v_add_f32_e32 v218, v242, v243
	v_pk_mul_f32 v[94:95], v[94:95], v[170:171]
	v_pk_mul_f32 v[96:97], v[96:97], v[172:173]
	v_pk_mul_f32 v[90:91], v[90:91], v[174:175]
	v_pk_mul_f32 v[92:93], v[92:93], v[176:177]
	v_cvt_pk_bf16_f32 v146, v94, v95
	v_cvt_pk_bf16_f32 v147, v96, v97
	v_cvt_pk_bf16_f32 v148, v90, v91
	v_cvt_pk_bf16_f32 v149, v92, v93
	s_add_u32 s40, s72, 0x10000
	s_addc_u32 s41, s73, 0
	global_store_dwordx4 v250, v[146:149], s[40:41] offset:0
	s_nop 1
	s_add_u32 s6, s94, 0x50000
	s_addc_u32 s7, s95, 0
	global_load_dwordx4 v[146:149], v250, s[6:7] offset:0
	v_lshlrev_b32_e32 v242, 16, v150
	v_and_b32_e32 v243, 0xffff0000, v150
	v_lshlrev_b32_e32 v244, 16, v151
	v_and_b32_e32 v245, 0xffff0000, v151
	v_lshlrev_b32_e32 v246, 16, v152
	v_and_b32_e32 v247, 0xffff0000, v152
	v_lshlrev_b32_e32 v248, 16, v153
	v_and_b32_e32 v249, 0xffff0000, v153
	v_pk_fma_f32 v[86:87], v[86:87], v[138:139], v[242:243]
	v_pk_fma_f32 v[88:89], v[88:89], v[140:141], v[244:245]
	v_pk_fma_f32 v[82:83], v[82:83], v[142:143], v[246:247]
	v_pk_fma_f32 v[84:85], v[84:85], v[144:145], v[248:249]
	v_cvt_pk_bf16_f32 v150, v86, v87
	v_cvt_pk_bf16_f32 v151, v88, v89
	v_cvt_pk_bf16_f32 v152, v82, v83
	v_cvt_pk_bf16_f32 v153, v84, v85
	s_add_u32 s6, s94, 0x10000
	s_addc_u32 s7, s95, 0
	global_store_dwordx4 v250, v[150:153], s[6:7] offset:256
	v_pk_mul_f32 v[242:243], v[86:87], v[86:87]
	v_pk_fma_f32 v[242:243], v[88:89], v[88:89], v[242:243]
	v_pk_fma_f32 v[242:243], v[82:83], v[82:83], v[242:243]
	v_pk_fma_f32 v[242:243], v[84:85], v[84:85], v[242:243]
	v_add_f32_e32 v242, v242, v243
	v_add_f32_e32 v218, v218, v242
	v_pk_mul_f32 v[86:87], v[86:87], v[178:179]
	v_pk_mul_f32 v[88:89], v[88:89], v[180:181]
	v_pk_mul_f32 v[82:83], v[82:83], v[182:183]
	v_pk_mul_f32 v[84:85], v[84:85], v[184:185]
	v_cvt_pk_bf16_f32 v150, v86, v87
	v_cvt_pk_bf16_f32 v151, v88, v89
	v_cvt_pk_bf16_f32 v152, v82, v83
	v_cvt_pk_bf16_f32 v153, v84, v85
	s_add_u32 s40, s72, 0x10000
	s_addc_u32 s41, s73, 0
	global_store_dwordx4 v250, v[150:153], s[40:41] offset:256
	s_nop 1
	s_add_u32 s6, s94, 0x50000
	s_addc_u32 s7, s95, 0
	global_load_dwordx4 v[150:153], v250, s[6:7] offset:256
	ds_bpermute_b32 v242, v219, v218
	s_waitcnt lgkmcnt(0)
	v_add_f32_e32 v218, v218, v242
	ds_bpermute_b32 v242, v241, v218
	s_waitcnt lgkmcnt(0)
	v_add_f32_e32 v218, v218, v242
	s_add_u32 s100, s50, 0x80
	s_addc_u32 s101, s51, 0
	s_and_saveexec_b64 s[40:41], s[98:99]
	global_atomic_add_f32 v251, v218, s[100:101]
	s_or_b64 exec, exec, s[40:41]
	v_lshlrev_b32_e32 v242, 16, v154
	v_and_b32_e32 v243, 0xffff0000, v154
	v_lshlrev_b32_e32 v244, 16, v155
	v_and_b32_e32 v245, 0xffff0000, v155
	v_lshlrev_b32_e32 v246, 16, v156
	v_and_b32_e32 v247, 0xffff0000, v156
	v_lshlrev_b32_e32 v248, 16, v157
	v_and_b32_e32 v249, 0xffff0000, v157
	v_pk_fma_f32 v[78:79], v[78:79], v[130:131], v[242:243]
	v_pk_fma_f32 v[80:81], v[80:81], v[132:133], v[244:245]
	v_pk_fma_f32 v[74:75], v[74:75], v[134:135], v[246:247]
	v_pk_fma_f32 v[76:77], v[76:77], v[136:137], v[248:249]
	v_cvt_pk_bf16_f32 v154, v78, v79
	v_cvt_pk_bf16_f32 v155, v80, v81
	v_cvt_pk_bf16_f32 v156, v74, v75
	v_cvt_pk_bf16_f32 v157, v76, v77
	s_add_u32 s6, s94, 0x18000
	s_addc_u32 s7, s95, 0
	global_store_dwordx4 v250, v[154:157], s[6:7] offset:0
	v_pk_mul_f32 v[242:243], v[78:79], v[78:79]
	v_pk_fma_f32 v[242:243], v[80:81], v[80:81], v[242:243]
	v_pk_fma_f32 v[242:243], v[74:75], v[74:75], v[242:243]
	v_pk_fma_f32 v[242:243], v[76:77], v[76:77], v[242:243]
	v_add_f32_e32 v218, v242, v243
	v_pk_mul_f32 v[78:79], v[78:79], v[170:171]
	v_pk_mul_f32 v[80:81], v[80:81], v[172:173]
	v_pk_mul_f32 v[74:75], v[74:75], v[174:175]
	v_pk_mul_f32 v[76:77], v[76:77], v[176:177]
	v_cvt_pk_bf16_f32 v154, v78, v79
	v_cvt_pk_bf16_f32 v155, v80, v81
	v_cvt_pk_bf16_f32 v156, v74, v75
	v_cvt_pk_bf16_f32 v157, v76, v77
	s_add_u32 s40, s72, 0x18000
	s_addc_u32 s41, s73, 0
	global_store_dwordx4 v250, v[154:157], s[40:41] offset:0
	s_nop 1
	s_add_u32 s6, s94, 0x58000
	s_addc_u32 s7, s95, 0
	global_load_dwordx4 v[154:157], v250, s[6:7] offset:0
	v_lshlrev_b32_e32 v242, 16, v210
	v_and_b32_e32 v243, 0xffff0000, v210
	v_lshlrev_b32_e32 v244, 16, v211
	v_and_b32_e32 v245, 0xffff0000, v211
	v_lshlrev_b32_e32 v246, 16, v212
	v_and_b32_e32 v247, 0xffff0000, v212
	v_lshlrev_b32_e32 v248, 16, v213
	v_and_b32_e32 v249, 0xffff0000, v213
	v_pk_fma_f32 v[70:71], v[70:71], v[138:139], v[242:243]
	v_pk_fma_f32 v[72:73], v[72:73], v[140:141], v[244:245]
	v_pk_fma_f32 v[66:67], v[66:67], v[142:143], v[246:247]
	v_pk_fma_f32 v[68:69], v[68:69], v[144:145], v[248:249]
	v_cvt_pk_bf16_f32 v210, v70, v71
	v_cvt_pk_bf16_f32 v211, v72, v73
	v_cvt_pk_bf16_f32 v212, v66, v67
	v_cvt_pk_bf16_f32 v213, v68, v69
	s_add_u32 s6, s94, 0x18000
	s_addc_u32 s7, s95, 0
	global_store_dwordx4 v250, v[210:213], s[6:7] offset:256
	v_pk_mul_f32 v[242:243], v[70:71], v[70:71]
	v_pk_fma_f32 v[242:243], v[72:73], v[72:73], v[242:243]
	v_pk_fma_f32 v[242:243], v[66:67], v[66:67], v[242:243]
	v_pk_fma_f32 v[242:243], v[68:69], v[68:69], v[242:243]
	v_add_f32_e32 v242, v242, v243
	v_add_f32_e32 v218, v218, v242
	v_pk_mul_f32 v[70:71], v[70:71], v[178:179]
	v_pk_mul_f32 v[72:73], v[72:73], v[180:181]
	v_pk_mul_f32 v[66:67], v[66:67], v[182:183]
	v_pk_mul_f32 v[68:69], v[68:69], v[184:185]
	v_cvt_pk_bf16_f32 v210, v70, v71
	v_cvt_pk_bf16_f32 v211, v72, v73
	v_cvt_pk_bf16_f32 v212, v66, v67
	v_cvt_pk_bf16_f32 v213, v68, v69
	s_add_u32 s40, s72, 0x18000
	s_addc_u32 s41, s73, 0
	global_store_dwordx4 v250, v[210:213], s[40:41] offset:256
	s_nop 1
	s_add_u32 s6, s94, 0x58000
	s_addc_u32 s7, s95, 0
	global_load_dwordx4 v[210:213], v250, s[6:7] offset:256
	ds_bpermute_b32 v242, v219, v218
	s_waitcnt lgkmcnt(0)
	v_add_f32_e32 v218, v218, v242
	ds_bpermute_b32 v242, v241, v218
	s_waitcnt lgkmcnt(0)
	v_add_f32_e32 v218, v218, v242
	s_add_u32 s100, s50, 0xc0
	s_addc_u32 s101, s51, 0
	s_and_saveexec_b64 s[40:41], s[98:99]
	global_atomic_add_f32 v251, v218, s[100:101]
	s_or_b64 exec, exec, s[40:41]
	s_waitcnt vmcnt(25)
	v_lshlrev_b32_e32 v242, 16, v186
	v_and_b32_e32 v243, 0xffff0000, v186
	v_lshlrev_b32_e32 v244, 16, v187
	v_and_b32_e32 v245, 0xffff0000, v187
	v_lshlrev_b32_e32 v246, 16, v188
	v_and_b32_e32 v247, 0xffff0000, v188
	v_lshlrev_b32_e32 v248, 16, v189
	v_and_b32_e32 v249, 0xffff0000, v189
	v_pk_fma_f32 v[62:63], v[62:63], v[130:131], v[242:243]
	v_pk_fma_f32 v[64:65], v[64:65], v[132:133], v[244:245]
	v_pk_fma_f32 v[58:59], v[58:59], v[134:135], v[246:247]
	v_pk_fma_f32 v[60:61], v[60:61], v[136:137], v[248:249]
	v_cvt_pk_bf16_f32 v186, v62, v63
	v_cvt_pk_bf16_f32 v187, v64, v65
	v_cvt_pk_bf16_f32 v188, v58, v59
	v_cvt_pk_bf16_f32 v189, v60, v61
	s_add_u32 s6, s94, 0x40000
	s_addc_u32 s7, s95, 0
	global_store_dwordx4 v250, v[186:189], s[6:7] offset:0
	v_pk_mul_f32 v[242:243], v[62:63], v[62:63]
	v_pk_fma_f32 v[242:243], v[64:65], v[64:65], v[242:243]
	v_pk_fma_f32 v[242:243], v[58:59], v[58:59], v[242:243]
	v_pk_fma_f32 v[242:243], v[60:61], v[60:61], v[242:243]
	v_add_f32_e32 v218, v242, v243
	v_pk_mul_f32 v[62:63], v[62:63], v[170:171]
	v_pk_mul_f32 v[64:65], v[64:65], v[172:173]
	v_pk_mul_f32 v[58:59], v[58:59], v[174:175]
	v_pk_mul_f32 v[60:61], v[60:61], v[176:177]
	v_cvt_pk_bf16_f32 v186, v62, v63
	v_cvt_pk_bf16_f32 v187, v64, v65
	v_cvt_pk_bf16_f32 v188, v58, v59
	v_cvt_pk_bf16_f32 v189, v60, v61
	s_add_u32 s40, s72, 0x40000
	s_addc_u32 s41, s73, 0
	global_store_dwordx4 v250, v[186:189], s[40:41] offset:0
	s_waitcnt vmcnt(24)
	v_lshlrev_b32_e32 v242, 16, v190
	v_and_b32_e32 v243, 0xffff0000, v190
	v_lshlrev_b32_e32 v244, 16, v191
	v_and_b32_e32 v245, 0xffff0000, v191
	v_lshlrev_b32_e32 v246, 16, v192
	v_and_b32_e32 v247, 0xffff0000, v192
	v_lshlrev_b32_e32 v248, 16, v193
	v_and_b32_e32 v249, 0xffff0000, v193
	v_pk_fma_f32 v[54:55], v[54:55], v[138:139], v[242:243]
	v_pk_fma_f32 v[56:57], v[56:57], v[140:141], v[244:245]
	v_pk_fma_f32 v[50:51], v[50:51], v[142:143], v[246:247]
	v_pk_fma_f32 v[52:53], v[52:53], v[144:145], v[248:249]
	v_cvt_pk_bf16_f32 v190, v54, v55
	v_cvt_pk_bf16_f32 v191, v56, v57
	v_cvt_pk_bf16_f32 v192, v50, v51
	v_cvt_pk_bf16_f32 v193, v52, v53
	s_add_u32 s6, s94, 0x40000
	s_addc_u32 s7, s95, 0
	global_store_dwordx4 v250, v[190:193], s[6:7] offset:256
	v_pk_mul_f32 v[242:243], v[54:55], v[54:55]
	v_pk_fma_f32 v[242:243], v[56:57], v[56:57], v[242:243]
	v_pk_fma_f32 v[242:243], v[50:51], v[50:51], v[242:243]
	v_pk_fma_f32 v[242:243], v[52:53], v[52:53], v[242:243]
	v_add_f32_e32 v242, v242, v243
	v_add_f32_e32 v218, v218, v242
	v_pk_mul_f32 v[54:55], v[54:55], v[178:179]
	v_pk_mul_f32 v[56:57], v[56:57], v[180:181]
	v_pk_mul_f32 v[50:51], v[50:51], v[182:183]
	v_pk_mul_f32 v[52:53], v[52:53], v[184:185]
	v_cvt_pk_bf16_f32 v190, v54, v55
	v_cvt_pk_bf16_f32 v191, v56, v57
	v_cvt_pk_bf16_f32 v192, v50, v51
	v_cvt_pk_bf16_f32 v193, v52, v53
	s_add_u32 s40, s72, 0x40000
	s_addc_u32 s41, s73, 0
	global_store_dwordx4 v250, v[190:193], s[40:41] offset:256
	ds_bpermute_b32 v242, v219, v218
	s_waitcnt lgkmcnt(0)
	v_add_f32_e32 v218, v218, v242
	ds_bpermute_b32 v242, v241, v218
	s_waitcnt lgkmcnt(0)
	v_add_f32_e32 v218, v218, v242
	s_add_u32 s100, s50, 0x200
	s_addc_u32 s101, s51, 0
	s_and_saveexec_b64 s[40:41], s[98:99]
	global_atomic_add_f32 v251, v218, s[100:101]
	s_or_b64 exec, exec, s[40:41]
	s_waitcnt vmcnt(23)
	v_lshlrev_b32_e32 v242, 16, v194
	v_and_b32_e32 v243, 0xffff0000, v194
	v_lshlrev_b32_e32 v244, 16, v195
	v_and_b32_e32 v245, 0xffff0000, v195
	v_lshlrev_b32_e32 v246, 16, v196
	v_and_b32_e32 v247, 0xffff0000, v196
	v_lshlrev_b32_e32 v248, 16, v197
	v_and_b32_e32 v249, 0xffff0000, v197
	v_pk_fma_f32 v[44:45], v[44:45], v[130:131], v[242:243]
	v_pk_fma_f32 v[46:47], v[46:47], v[132:133], v[244:245]
	v_pk_fma_f32 v[40:41], v[40:41], v[134:135], v[246:247]
	v_pk_fma_f32 v[42:43], v[42:43], v[136:137], v[248:249]
	v_cvt_pk_bf16_f32 v194, v44, v45
	v_cvt_pk_bf16_f32 v195, v46, v47
	v_cvt_pk_bf16_f32 v196, v40, v41
	v_cvt_pk_bf16_f32 v197, v42, v43
	s_add_u32 s6, s94, 0x48000
	s_addc_u32 s7, s95, 0
	global_store_dwordx4 v250, v[194:197], s[6:7] offset:0
	v_pk_mul_f32 v[242:243], v[44:45], v[44:45]
	v_pk_fma_f32 v[242:243], v[46:47], v[46:47], v[242:243]
	v_pk_fma_f32 v[242:243], v[40:41], v[40:41], v[242:243]
	v_pk_fma_f32 v[242:243], v[42:43], v[42:43], v[242:243]
	v_add_f32_e32 v218, v242, v243
	v_pk_mul_f32 v[44:45], v[44:45], v[170:171]
	v_pk_mul_f32 v[46:47], v[46:47], v[172:173]
	v_pk_mul_f32 v[40:41], v[40:41], v[174:175]
	v_pk_mul_f32 v[42:43], v[42:43], v[176:177]
	v_cvt_pk_bf16_f32 v194, v44, v45
	v_cvt_pk_bf16_f32 v195, v46, v47
	v_cvt_pk_bf16_f32 v196, v40, v41
	v_cvt_pk_bf16_f32 v197, v42, v43
	s_add_u32 s40, s72, 0x48000
	s_addc_u32 s41, s73, 0
	global_store_dwordx4 v250, v[194:197], s[40:41] offset:0
	s_waitcnt vmcnt(22)
	v_lshlrev_b32_e32 v242, 16, v198
	v_and_b32_e32 v243, 0xffff0000, v198
	v_lshlrev_b32_e32 v244, 16, v199
	v_and_b32_e32 v245, 0xffff0000, v199
	v_lshlrev_b32_e32 v246, 16, v200
	v_and_b32_e32 v247, 0xffff0000, v200
	v_lshlrev_b32_e32 v248, 16, v201
	v_and_b32_e32 v249, 0xffff0000, v201
	v_pk_fma_f32 v[36:37], v[36:37], v[138:139], v[242:243]
	v_pk_fma_f32 v[38:39], v[38:39], v[140:141], v[244:245]
	v_pk_fma_f32 v[32:33], v[32:33], v[142:143], v[246:247]
	v_pk_fma_f32 v[34:35], v[34:35], v[144:145], v[248:249]
	v_cvt_pk_bf16_f32 v198, v36, v37
	v_cvt_pk_bf16_f32 v199, v38, v39
	v_cvt_pk_bf16_f32 v200, v32, v33
	v_cvt_pk_bf16_f32 v201, v34, v35
	s_add_u32 s6, s94, 0x48000
	s_addc_u32 s7, s95, 0
	global_store_dwordx4 v250, v[198:201], s[6:7] offset:256
	v_pk_mul_f32 v[242:243], v[36:37], v[36:37]
	v_pk_fma_f32 v[242:243], v[38:39], v[38:39], v[242:243]
	v_pk_fma_f32 v[242:243], v[32:33], v[32:33], v[242:243]
	v_pk_fma_f32 v[242:243], v[34:35], v[34:35], v[242:243]
	v_add_f32_e32 v242, v242, v243
	v_add_f32_e32 v218, v218, v242
	v_pk_mul_f32 v[36:37], v[36:37], v[178:179]
	v_pk_mul_f32 v[38:39], v[38:39], v[180:181]
	v_pk_mul_f32 v[32:33], v[32:33], v[182:183]
	v_pk_mul_f32 v[34:35], v[34:35], v[184:185]
	v_cvt_pk_bf16_f32 v198, v36, v37
	v_cvt_pk_bf16_f32 v199, v38, v39
	v_cvt_pk_bf16_f32 v200, v32, v33
	v_cvt_pk_bf16_f32 v201, v34, v35
	s_add_u32 s40, s72, 0x48000
	s_addc_u32 s41, s73, 0
	global_store_dwordx4 v250, v[198:201], s[40:41] offset:256
	ds_bpermute_b32 v242, v219, v218
	s_waitcnt lgkmcnt(0)
	v_add_f32_e32 v218, v218, v242
	ds_bpermute_b32 v242, v241, v218
	s_waitcnt lgkmcnt(0)
	v_add_f32_e32 v218, v218, v242
	s_add_u32 s100, s50, 0x240
	s_addc_u32 s101, s51, 0
	s_and_saveexec_b64 s[40:41], s[98:99]
	global_atomic_add_f32 v251, v218, s[100:101]
	s_or_b64 exec, exec, s[40:41]
	s_waitcnt vmcnt(21)
	v_lshlrev_b32_e32 v242, 16, v146
	v_and_b32_e32 v243, 0xffff0000, v146
	v_lshlrev_b32_e32 v244, 16, v147
	v_and_b32_e32 v245, 0xffff0000, v147
	v_lshlrev_b32_e32 v246, 16, v148
	v_and_b32_e32 v247, 0xffff0000, v148
	v_lshlrev_b32_e32 v248, 16, v149
	v_and_b32_e32 v249, 0xffff0000, v149
	v_pk_fma_f32 v[28:29], v[28:29], v[130:131], v[242:243]
	v_pk_fma_f32 v[30:31], v[30:31], v[132:133], v[244:245]
	v_pk_fma_f32 v[24:25], v[24:25], v[134:135], v[246:247]
	v_pk_fma_f32 v[26:27], v[26:27], v[136:137], v[248:249]
	v_cvt_pk_bf16_f32 v146, v28, v29
	v_cvt_pk_bf16_f32 v147, v30, v31
	v_cvt_pk_bf16_f32 v148, v24, v25
	v_cvt_pk_bf16_f32 v149, v26, v27
	s_add_u32 s6, s94, 0x50000
	s_addc_u32 s7, s95, 0
	global_store_dwordx4 v250, v[146:149], s[6:7] offset:0
	v_pk_mul_f32 v[242:243], v[28:29], v[28:29]
	v_pk_fma_f32 v[242:243], v[30:31], v[30:31], v[242:243]
	v_pk_fma_f32 v[242:243], v[24:25], v[24:25], v[242:243]
	v_pk_fma_f32 v[242:243], v[26:27], v[26:27], v[242:243]
	v_add_f32_e32 v218, v242, v243
	v_pk_mul_f32 v[28:29], v[28:29], v[170:171]
	v_pk_mul_f32 v[30:31], v[30:31], v[172:173]
	v_pk_mul_f32 v[24:25], v[24:25], v[174:175]
	v_pk_mul_f32 v[26:27], v[26:27], v[176:177]
	v_cvt_pk_bf16_f32 v146, v28, v29
	v_cvt_pk_bf16_f32 v147, v30, v31
	v_cvt_pk_bf16_f32 v148, v24, v25
	v_cvt_pk_bf16_f32 v149, v26, v27
	s_add_u32 s40, s72, 0x50000
	s_addc_u32 s41, s73, 0
	global_store_dwordx4 v250, v[146:149], s[40:41] offset:0
	s_waitcnt vmcnt(20)
	v_lshlrev_b32_e32 v242, 16, v150
	v_and_b32_e32 v243, 0xffff0000, v150
	v_lshlrev_b32_e32 v244, 16, v151
	v_and_b32_e32 v245, 0xffff0000, v151
	v_lshlrev_b32_e32 v246, 16, v152
	v_and_b32_e32 v247, 0xffff0000, v152
	v_lshlrev_b32_e32 v248, 16, v153
	v_and_b32_e32 v249, 0xffff0000, v153
	v_pk_fma_f32 v[20:21], v[20:21], v[138:139], v[242:243]
	v_pk_fma_f32 v[22:23], v[22:23], v[140:141], v[244:245]
	v_pk_fma_f32 v[16:17], v[16:17], v[142:143], v[246:247]
	v_pk_fma_f32 v[18:19], v[18:19], v[144:145], v[248:249]
	v_cvt_pk_bf16_f32 v150, v20, v21
	v_cvt_pk_bf16_f32 v151, v22, v23
	v_cvt_pk_bf16_f32 v152, v16, v17
	v_cvt_pk_bf16_f32 v153, v18, v19
	s_add_u32 s6, s94, 0x50000
	s_addc_u32 s7, s95, 0
	global_store_dwordx4 v250, v[150:153], s[6:7] offset:256
	v_pk_mul_f32 v[242:243], v[20:21], v[20:21]
	v_pk_fma_f32 v[242:243], v[22:23], v[22:23], v[242:243]
	v_pk_fma_f32 v[242:243], v[16:17], v[16:17], v[242:243]
	v_pk_fma_f32 v[242:243], v[18:19], v[18:19], v[242:243]
	v_add_f32_e32 v242, v242, v243
	v_add_f32_e32 v218, v218, v242
	v_pk_mul_f32 v[20:21], v[20:21], v[178:179]
	v_pk_mul_f32 v[22:23], v[22:23], v[180:181]
	v_pk_mul_f32 v[16:17], v[16:17], v[182:183]
	v_pk_mul_f32 v[18:19], v[18:19], v[184:185]
	v_cvt_pk_bf16_f32 v150, v20, v21
	v_cvt_pk_bf16_f32 v151, v22, v23
	v_cvt_pk_bf16_f32 v152, v16, v17
	v_cvt_pk_bf16_f32 v153, v18, v19
	s_add_u32 s40, s72, 0x50000
	s_addc_u32 s41, s73, 0
	global_store_dwordx4 v250, v[150:153], s[40:41] offset:256
	ds_bpermute_b32 v242, v219, v218
	s_waitcnt lgkmcnt(0)
	v_add_f32_e32 v218, v218, v242
	ds_bpermute_b32 v242, v241, v218
	s_waitcnt lgkmcnt(0)
	v_add_f32_e32 v218, v218, v242
	s_add_u32 s100, s50, 0x280
	s_addc_u32 s101, s51, 0
	s_and_saveexec_b64 s[40:41], s[98:99]
	global_atomic_add_f32 v251, v218, s[100:101]
	s_or_b64 exec, exec, s[40:41]
	s_waitcnt vmcnt(19)
	v_lshlrev_b32_e32 v242, 16, v154
	v_and_b32_e32 v243, 0xffff0000, v154
	v_lshlrev_b32_e32 v244, 16, v155
	v_and_b32_e32 v245, 0xffff0000, v155
	v_lshlrev_b32_e32 v246, 16, v156
	v_and_b32_e32 v247, 0xffff0000, v156
	v_lshlrev_b32_e32 v248, 16, v157
	v_and_b32_e32 v249, 0xffff0000, v157
	v_pk_fma_f32 v[12:13], v[12:13], v[130:131], v[242:243]
	v_pk_fma_f32 v[14:15], v[14:15], v[132:133], v[244:245]
	v_pk_fma_f32 v[8:9], v[8:9], v[134:135], v[246:247]
	v_pk_fma_f32 v[10:11], v[10:11], v[136:137], v[248:249]
	v_cvt_pk_bf16_f32 v154, v12, v13
	v_cvt_pk_bf16_f32 v155, v14, v15
	v_cvt_pk_bf16_f32 v156, v8, v9
	v_cvt_pk_bf16_f32 v157, v10, v11
	s_add_u32 s6, s94, 0x58000
	s_addc_u32 s7, s95, 0
	global_store_dwordx4 v250, v[154:157], s[6:7] offset:0
	v_pk_mul_f32 v[242:243], v[12:13], v[12:13]
	v_pk_fma_f32 v[242:243], v[14:15], v[14:15], v[242:243]
	v_pk_fma_f32 v[242:243], v[8:9], v[8:9], v[242:243]
	v_pk_fma_f32 v[242:243], v[10:11], v[10:11], v[242:243]
	v_add_f32_e32 v218, v242, v243
	v_pk_mul_f32 v[12:13], v[12:13], v[170:171]
	v_pk_mul_f32 v[14:15], v[14:15], v[172:173]
	v_pk_mul_f32 v[8:9], v[8:9], v[174:175]
	v_pk_mul_f32 v[10:11], v[10:11], v[176:177]
	v_cvt_pk_bf16_f32 v154, v12, v13
	v_cvt_pk_bf16_f32 v155, v14, v15
	v_cvt_pk_bf16_f32 v156, v8, v9
	v_cvt_pk_bf16_f32 v157, v10, v11
	s_add_u32 s40, s72, 0x58000
	s_addc_u32 s41, s73, 0
	global_store_dwordx4 v250, v[154:157], s[40:41] offset:0
	s_waitcnt vmcnt(18)
	v_lshlrev_b32_e32 v242, 16, v210
	v_and_b32_e32 v243, 0xffff0000, v210
	v_lshlrev_b32_e32 v244, 16, v211
	v_and_b32_e32 v245, 0xffff0000, v211
	v_lshlrev_b32_e32 v246, 16, v212
	v_and_b32_e32 v247, 0xffff0000, v212
	v_lshlrev_b32_e32 v248, 16, v213
	v_and_b32_e32 v249, 0xffff0000, v213
	v_pk_fma_f32 v[4:5], v[4:5], v[138:139], v[242:243]
	v_pk_fma_f32 v[6:7], v[6:7], v[140:141], v[244:245]
	v_pk_fma_f32 v[0:1], v[0:1], v[142:143], v[246:247]
	v_pk_fma_f32 v[2:3], v[2:3], v[144:145], v[248:249]
	v_cvt_pk_bf16_f32 v210, v4, v5
	v_cvt_pk_bf16_f32 v211, v6, v7
	v_cvt_pk_bf16_f32 v212, v0, v1
	v_cvt_pk_bf16_f32 v213, v2, v3
	s_add_u32 s6, s94, 0x58000
	s_addc_u32 s7, s95, 0
	global_store_dwordx4 v250, v[210:213], s[6:7] offset:256
	v_pk_mul_f32 v[242:243], v[4:5], v[4:5]
	v_pk_fma_f32 v[242:243], v[6:7], v[6:7], v[242:243]
	v_pk_fma_f32 v[242:243], v[0:1], v[0:1], v[242:243]
	v_pk_fma_f32 v[242:243], v[2:3], v[2:3], v[242:243]
	v_add_f32_e32 v242, v242, v243
	v_add_f32_e32 v218, v218, v242
	v_pk_mul_f32 v[4:5], v[4:5], v[178:179]
	v_pk_mul_f32 v[6:7], v[6:7], v[180:181]
	v_pk_mul_f32 v[0:1], v[0:1], v[182:183]
	v_pk_mul_f32 v[2:3], v[2:3], v[184:185]
	v_cvt_pk_bf16_f32 v210, v4, v5
	v_cvt_pk_bf16_f32 v211, v6, v7
	v_cvt_pk_bf16_f32 v212, v0, v1
	v_cvt_pk_bf16_f32 v213, v2, v3
	s_add_u32 s40, s72, 0x58000
	s_addc_u32 s41, s73, 0
	global_store_dwordx4 v250, v[210:213], s[40:41] offset:256
	ds_bpermute_b32 v242, v219, v218
	s_waitcnt lgkmcnt(0)
	v_add_f32_e32 v218, v218, v242
	ds_bpermute_b32 v242, v241, v218
	s_waitcnt lgkmcnt(0)
	v_add_f32_e32 v218, v218, v242
	s_add_u32 s100, s50, 0x2c0
	s_addc_u32 s101, s51, 0
	s_and_saveexec_b64 s[40:41], s[98:99]
	global_atomic_add_f32 v251, v218, s[100:101]
	s_or_b64 exec, exec, s[40:41]
	s_branch .LBB0_991
.Leo_nonext:
	s_ashr_i32 s6, s37, 3
	s_mul_i32 s6, s6, 0xc000
	s_add_u32 s6, s46, s6
	s_addc_u32 s7, s47, 0
	s_add_i32 s8, s8, s29
	v_add_u32_e32 v251, s8, v207
	v_lshlrev_b32_e32 v250, 11, v251
	v_lshl_add_u32 v250, v168, 1, v250
	v_lshlrev_b32_e32 v251, 2, v251
	v_lshlrev_b32_e32 v242, 2, v168
	v_add_u32_e32 v243, 0x2000, v242
	v_add_u32_e32 v244, 0x4000, v242
	global_load_dwordx4 v[130:133], v243, s[6:7] offset:0
	global_load_dwordx4 v[134:137], v243, s[6:7] offset:16
	global_load_dwordx4 v[138:141], v243, s[6:7] offset:512
	global_load_dwordx4 v[142:145], v243, s[6:7] offset:528
	v_xor_b32_e32 v219, 16, v233
	v_lshlrev_b32_e32 v219, 2, v219
	v_xor_b32_e32 v241, 32, v233
	v_lshlrev_b32_e32 v241, 2, v241
	v_cmp_eq_u32_e64 s[98:99], 0, v217
	s_add_u32 s6, s94, 0x0
	s_addc_u32 s7, s95, 0
	global_load_dwordx4 v[186:189], v250, s[6:7] offset:0
	global_load_dwordx4 v[190:193], v250, s[6:7] offset:256
	s_add_u32 s6, s94, 0x8000
	s_addc_u32 s7, s95, 0
	global_load_dwordx4 v[194:197], v250, s[6:7] offset:0
	global_load_dwordx4 v[198:201], v250, s[6:7] offset:256
	s_add_u32 s6, s94, 0x10000
	s_addc_u32 s7, s95, 0
	global_load_dwordx4 v[146:149], v250, s[6:7] offset:0
	global_load_dwordx4 v[150:153], v250, s[6:7] offset:256
	s_add_u32 s6, s94, 0x18000
	s_addc_u32 s7, s95, 0
	global_load_dwordx4 v[154:157], v250, s[6:7] offset:0
	global_load_dwordx4 v[210:213], v250, s[6:7] offset:256
	s_waitcnt vmcnt(8)
	v_pk_add_f32 v[130:131], v[130:131], 1.0 op_sel_hi:[1,0]
	v_pk_add_f32 v[132:133], v[132:133], 1.0 op_sel_hi:[1,0]
	v_pk_add_f32 v[134:135], v[134:135], 1.0 op_sel_hi:[1,0]
	v_pk_add_f32 v[136:137], v[136:137], 1.0 op_sel_hi:[1,0]
	v_pk_add_f32 v[138:139], v[138:139], 1.0 op_sel_hi:[1,0]
	v_pk_add_f32 v[140:141], v[140:141], 1.0 op_sel_hi:[1,0]
	v_pk_add_f32 v[142:143], v[142:143], 1.0 op_sel_hi:[1,0]
	v_pk_add_f32 v[144:145], v[144:145], 1.0 op_sel_hi:[1,0]
	s_waitcnt vmcnt(7)
	v_lshlrev_b32_e32 v242, 16, v186
	v_and_b32_e32 v243, 0xffff0000, v186
	v_lshlrev_b32_e32 v244, 16, v187
	v_and_b32_e32 v245, 0xffff0000, v187
	v_lshlrev_b32_e32 v246, 16, v188
	v_and_b32_e32 v247, 0xffff0000, v188
	v_lshlrev_b32_e32 v248, 16, v189
	v_and_b32_e32 v249, 0xffff0000, v189
	v_pk_fma_f32 v[126:127], v[126:127], v[130:131], v[242:243]
	v_pk_fma_f32 v[128:129], v[128:129], v[132:133], v[244:245]
	v_pk_fma_f32 v[122:123], v[122:123], v[134:135], v[246:247]
	v_pk_fma_f32 v[124:125], v[124:125], v[136:137], v[248:249]
	v_cvt_pk_bf16_f32 v186, v126, v127
	v_cvt_pk_bf16_f32 v187, v128, v129
	v_cvt_pk_bf16_f32 v188, v122, v123
	v_cvt_pk_bf16_f32 v189, v124, v125
	s_add_u32 s6, s94, 0x0
	s_addc_u32 s7, s95, 0
	global_store_dwordx4 v250, v[186:189], s[6:7] offset:0
	v_pk_mul_f32 v[242:243], v[126:127], v[126:127]
	v_pk_fma_f32 v[242:243], v[128:129], v[128:129], v[242:243]
	v_pk_fma_f32 v[242:243], v[122:123], v[122:123], v[242:243]
	v_pk_fma_f32 v[242:243], v[124:125], v[124:125], v[242:243]
	v_add_f32_e32 v218, v242, v243
	s_nop 1
	s_add_u32 s6, s94, 0x40000
	s_addc_u32 s7, s95, 0
	global_load_dwordx4 v[186:189], v250, s[6:7] offset:0
	s_waitcnt vmcnt(8)
	v_lshlrev_b32_e32 v242, 16, v190
	v_and_b32_e32 v243, 0xffff0000, v190
	v_lshlrev_b32_e32 v244, 16, v191
	v_and_b32_e32 v245, 0xffff0000, v191
	v_lshlrev_b32_e32 v246, 16, v192
	v_and_b32_e32 v247, 0xffff0000, v192
	v_lshlrev_b32_e32 v248, 16, v193
	v_and_b32_e32 v249, 0xffff0000, v193
	v_pk_fma_f32 v[118:119], v[118:119], v[138:139], v[242:243]
	v_pk_fma_f32 v[120:121], v[120:121], v[140:141], v[244:245]
	v_pk_fma_f32 v[114:115], v[114:115], v[142:143], v[246:247]
	v_pk_fma_f32 v[116:117], v[116:117], v[144:145], v[248:249]
	v_cvt_pk_bf16_f32 v190, v118, v119
	v_cvt_pk_bf16_f32 v191, v120, v121
	v_cvt_pk_bf16_f32 v192, v114, v115
	v_cvt_pk_bf16_f32 v193, v116, v117
	s_add_u32 s6, s94, 0x0
	s_addc_u32 s7, s95, 0
	global_store_dwordx4 v250, v[190:193], s[6:7] offset:256
	v_pk_mul_f32 v[242:243], v[118:119], v[118:119]
	v_pk_fma_f32 v[242:243], v[120:121], v[120:121], v[242:243]
	v_pk_fma_f32 v[242:243], v[114:115], v[114:115], v[242:243]
	v_pk_fma_f32 v[242:243], v[116:117], v[116:117], v[242:243]
	v_add_f32_e32 v242, v242, v243
	v_add_f32_e32 v218, v218, v242
	s_nop 1
	s_add_u32 s6, s94, 0x40000
	s_addc_u32 s7, s95, 0
	global_load_dwordx4 v[190:193], v250, s[6:7] offset:256
	ds_bpermute_b32 v242, v219, v218
	s_waitcnt lgkmcnt(0)
	v_add_f32_e32 v218, v218, v242
	ds_bpermute_b32 v242, v241, v218
	s_waitcnt lgkmcnt(0)
	v_add_f32_e32 v218, v218, v242
	s_add_u32 s100, s50, 0x0
	s_addc_u32 s101, s51, 0
	s_and_saveexec_b64 s[40:41], s[98:99]
	global_atomic_add_f32 v251, v218, s[100:101]
	s_or_b64 exec, exec, s[40:41]
	s_waitcnt vmcnt(10)
	v_lshlrev_b32_e32 v242, 16, v194
	v_and_b32_e32 v243, 0xffff0000, v194
	v_lshlrev_b32_e32 v244, 16, v195
	v_and_b32_e32 v245, 0xffff0000, v195
	v_lshlrev_b32_e32 v246, 16, v196
	v_and_b32_e32 v247, 0xffff0000, v196
	v_lshlrev_b32_e32 v248, 16, v197
	v_and_b32_e32 v249, 0xffff0000, v197
	v_pk_fma_f32 v[110:111], v[110:111], v[130:131], v[242:243]
	v_pk_fma_f32 v[112:113], v[112:113], v[132:133], v[244:245]
	v_pk_fma_f32 v[106:107], v[106:107], v[134:135], v[246:247]
	v_pk_fma_f32 v[108:109], v[108:109], v[136:137], v[248:249]
	v_cvt_pk_bf16_f32 v194, v110, v111
	v_cvt_pk_bf16_f32 v195, v112, v113
	v_cvt_pk_bf16_f32 v196, v106, v107
	v_cvt_pk_bf16_f32 v197, v108, v109
	s_add_u32 s6, s94, 0x8000
	s_addc_u32 s7, s95, 0
	global_store_dwordx4 v250, v[194:197], s[6:7] offset:0
	v_pk_mul_f32 v[242:243], v[110:111], v[110:111]
	v_pk_fma_f32 v[242:243], v[112:113], v[112:113], v[242:243]
	v_pk_fma_f32 v[242:243], v[106:107], v[106:107], v[242:243]
	v_pk_fma_f32 v[242:243], v[108:109], v[108:109], v[242:243]
	v_add_f32_e32 v218, v242, v243
	s_nop 1
	s_add_u32 s6, s94, 0x48000
	s_addc_u32 s7, s95, 0
	global_load_dwordx4 v[194:197], v250, s[6:7] offset:0
	s_waitcnt vmcnt(11)
	v_lshlrev_b32_e32 v242, 16, v198
	v_and_b32_e32 v243, 0xffff0000, v198
	v_lshlrev_b32_e32 v244, 16, v199
	v_and_b32_e32 v245, 0xffff0000, v199
	v_lshlrev_b32_e32 v246, 16, v200
	v_and_b32_e32 v247, 0xffff0000, v200
	v_lshlrev_b32_e32 v248, 16, v201
	v_and_b32_e32 v249, 0xffff0000, v201
	v_pk_fma_f32 v[102:103], v[102:103], v[138:139], v[242:243]
	v_pk_fma_f32 v[104:105], v[104:105], v[140:141], v[244:245]
	v_pk_fma_f32 v[98:99], v[98:99], v[142:143], v[246:247]
	v_pk_fma_f32 v[100:101], v[100:101], v[144:145], v[248:249]
	v_cvt_pk_bf16_f32 v198, v102, v103
	v_cvt_pk_bf16_f32 v199, v104, v105
	v_cvt_pk_bf16_f32 v200, v98, v99
	v_cvt_pk_bf16_f32 v201, v100, v101
	s_add_u32 s6, s94, 0x8000
	s_addc_u32 s7, s95, 0
	global_store_dwordx4 v250, v[198:201], s[6:7] offset:256
	v_pk_mul_f32 v[242:243], v[102:103], v[102:103]
	v_pk_fma_f32 v[242:243], v[104:105], v[104:105], v[242:243]
	v_pk_fma_f32 v[242:243], v[98:99], v[98:99], v[242:243]
	v_pk_fma_f32 v[242:243], v[100:101], v[100:101], v[242:243]
	v_add_f32_e32 v242, v242, v243
	v_add_f32_e32 v218, v218, v242
	s_nop 1
	s_add_u32 s6, s94, 0x48000
	s_addc_u32 s7, s95, 0
	global_load_dwordx4 v[198:201], v250, s[6:7] offset:256
	ds_bpermute_b32 v242, v219, v218
	s_waitcnt lgkmcnt(0)
	v_add_f32_e32 v218, v218, v242
	ds_bpermute_b32 v242, v241, v218
	s_waitcnt lgkmcnt(0)
	v_add_f32_e32 v218, v218, v242
	s_add_u32 s100, s50, 0x40
	s_addc_u32 s101, s51, 0
	s_and_saveexec_b64 s[40:41], s[98:99]
	global_atomic_add_f32 v251, v218, s[100:101]
	s_or_b64 exec, exec, s[40:41]
	s_waitcnt vmcnt(13)
	v_lshlrev_b32_e32 v242, 16, v146
	v_and_b32_e32 v243, 0xffff0000, v146
	v_lshlrev_b32_e32 v244, 16, v147
	v_and_b32_e32 v245, 0xffff0000, v147
	v_lshlrev_b32_e32 v246, 16, v148
	v_and_b32_e32 v247, 0xffff0000, v148
	v_lshlrev_b32_e32 v248, 16, v149
	v_and_b32_e32 v249, 0xffff0000, v149
	v_pk_fma_f32 v[94:95], v[94:95], v[130:131], v[242:243]
	v_pk_fma_f32 v[96:97], v[96:97], v[132:133], v[244:245]
	v_pk_fma_f32 v[90:91], v[90:91], v[134:135], v[246:247]
	v_pk_fma_f32 v[92:93], v[92:93], v[136:137], v[248:249]
	v_cvt_pk_bf16_f32 v146, v94, v95
	v_cvt_pk_bf16_f32 v147, v96, v97
	v_cvt_pk_bf16_f32 v148, v90, v91
	v_cvt_pk_bf16_f32 v149, v92, v93
	s_add_u32 s6, s94, 0x10000
	s_addc_u32 s7, s95, 0
	global_store_dwordx4 v250, v[146:149], s[6:7] offset:0
	v_pk_mul_f32 v[242:243], v[94:95], v[94:95]
	v_pk_fma_f32 v[242:243], v[96:97], v[96:97], v[242:243]
	v_pk_fma_f32 v[242:243], v[90:91], v[90:91], v[242:243]
	v_pk_fma_f32 v[242:243], v[92:93], v[92:93], v[242:243]
	v_add_f32_e32 v218, v242, v243
	s_nop 1
	s_add_u32 s6, s94, 0x50000
	s_addc_u32 s7, s95, 0
	global_load_dwordx4 v[146:149], v250, s[6:7] offset:0
	s_waitcnt vmcnt(14)
	v_lshlrev_b32_e32 v242, 16, v150
	v_and_b32_e32 v243, 0xffff0000, v150
	v_lshlrev_b32_e32 v244, 16, v151
	v_and_b32_e32 v245, 0xffff0000, v151
	v_lshlrev_b32_e32 v246, 16, v152
	v_and_b32_e32 v247, 0xffff0000, v152
	v_lshlrev_b32_e32 v248, 16, v153
	v_and_b32_e32 v249, 0xffff0000, v153
	v_pk_fma_f32 v[86:87], v[86:87], v[138:139], v[242:243]
	v_pk_fma_f32 v[88:89], v[88:89], v[140:141], v[244:245]
	v_pk_fma_f32 v[82:83], v[82:83], v[142:143], v[246:247]
	v_pk_fma_f32 v[84:85], v[84:85], v[144:145], v[248:249]
	v_cvt_pk_bf16_f32 v150, v86, v87
	v_cvt_pk_bf16_f32 v151, v88, v89
	v_cvt_pk_bf16_f32 v152, v82, v83
	v_cvt_pk_bf16_f32 v153, v84, v85
	s_add_u32 s6, s94, 0x10000
	s_addc_u32 s7, s95, 0
	global_store_dwordx4 v250, v[150:153], s[6:7] offset:256
	v_pk_mul_f32 v[242:243], v[86:87], v[86:87]
	v_pk_fma_f32 v[242:243], v[88:89], v[88:89], v[242:243]
	v_pk_fma_f32 v[242:243], v[82:83], v[82:83], v[242:243]
	v_pk_fma_f32 v[242:243], v[84:85], v[84:85], v[242:243]
	v_add_f32_e32 v242, v242, v243
	v_add_f32_e32 v218, v218, v242
	s_nop 1
	s_add_u32 s6, s94, 0x50000
	s_addc_u32 s7, s95, 0
	global_load_dwordx4 v[150:153], v250, s[6:7] offset:256
	ds_bpermute_b32 v242, v219, v218
	s_waitcnt lgkmcnt(0)
	v_add_f32_e32 v218, v218, v242
	ds_bpermute_b32 v242, v241, v218
	s_waitcnt lgkmcnt(0)
	v_add_f32_e32 v218, v218, v242
	s_add_u32 s100, s50, 0x80
	s_addc_u32 s101, s51, 0
	s_and_saveexec_b64 s[40:41], s[98:99]
	global_atomic_add_f32 v251, v218, s[100:101]
	s_or_b64 exec, exec, s[40:41]
	s_waitcnt vmcnt(16)
	v_lshlrev_b32_e32 v242, 16, v154
	v_and_b32_e32 v243, 0xffff0000, v154
	v_lshlrev_b32_e32 v244, 16, v155
	v_and_b32_e32 v245, 0xffff0000, v155
	v_lshlrev_b32_e32 v246, 16, v156
	v_and_b32_e32 v247, 0xffff0000, v156
	v_lshlrev_b32_e32 v248, 16, v157
	v_and_b32_e32 v249, 0xffff0000, v157
	v_pk_fma_f32 v[78:79], v[78:79], v[130:131], v[242:243]
	v_pk_fma_f32 v[80:81], v[80:81], v[132:133], v[244:245]
	v_pk_fma_f32 v[74:75], v[74:75], v[134:135], v[246:247]
	v_pk_fma_f32 v[76:77], v[76:77], v[136:137], v[248:249]
	v_cvt_pk_bf16_f32 v154, v78, v79
	v_cvt_pk_bf16_f32 v155, v80, v81
	v_cvt_pk_bf16_f32 v156, v74, v75
	v_cvt_pk_bf16_f32 v157, v76, v77
	s_add_u32 s6, s94, 0x18000
	s_addc_u32 s7, s95, 0
	global_store_dwordx4 v250, v[154:157], s[6:7] offset:0
	v_pk_mul_f32 v[242:243], v[78:79], v[78:79]
	v_pk_fma_f32 v[242:243], v[80:81], v[80:81], v[242:243]
	v_pk_fma_f32 v[242:243], v[74:75], v[74:75], v[242:243]
	v_pk_fma_f32 v[242:243], v[76:77], v[76:77], v[242:243]
	v_add_f32_e32 v218, v242, v243
	s_nop 1
	s_add_u32 s6, s94, 0x58000
	s_addc_u32 s7, s95, 0
	global_load_dwordx4 v[154:157], v250, s[6:7] offset:0
	s_waitcnt vmcnt(17)
	v_lshlrev_b32_e32 v242, 16, v210
	v_and_b32_e32 v243, 0xffff0000, v210
	v_lshlrev_b32_e32 v244, 16, v211
	v_and_b32_e32 v245, 0xffff0000, v211
	v_lshlrev_b32_e32 v246, 16, v212
	v_and_b32_e32 v247, 0xffff0000, v212
	v_lshlrev_b32_e32 v248, 16, v213
	v_and_b32_e32 v249, 0xffff0000, v213
	v_pk_fma_f32 v[70:71], v[70:71], v[138:139], v[242:243]
	v_pk_fma_f32 v[72:73], v[72:73], v[140:141], v[244:245]
	v_pk_fma_f32 v[66:67], v[66:67], v[142:143], v[246:247]
	v_pk_fma_f32 v[68:69], v[68:69], v[144:145], v[248:249]
	v_cvt_pk_bf16_f32 v210, v70, v71
	v_cvt_pk_bf16_f32 v211, v72, v73
	v_cvt_pk_bf16_f32 v212, v66, v67
	v_cvt_pk_bf16_f32 v213, v68, v69
	s_add_u32 s6, s94, 0x18000
	s_addc_u32 s7, s95, 0
	global_store_dwordx4 v250, v[210:213], s[6:7] offset:256
	v_pk_mul_f32 v[242:243], v[70:71], v[70:71]
	v_pk_fma_f32 v[242:243], v[72:73], v[72:73], v[242:243]
	v_pk_fma_f32 v[242:243], v[66:67], v[66:67], v[242:243]
	v_pk_fma_f32 v[242:243], v[68:69], v[68:69], v[242:243]
	v_add_f32_e32 v242, v242, v243
	v_add_f32_e32 v218, v218, v242
	s_nop 1
	s_add_u32 s6, s94, 0x58000
	s_addc_u32 s7, s95, 0
	global_load_dwordx4 v[210:213], v250, s[6:7] offset:256
	ds_bpermute_b32 v242, v219, v218
	s_waitcnt lgkmcnt(0)
	v_add_f32_e32 v218, v218, v242
	ds_bpermute_b32 v242, v241, v218
	s_waitcnt lgkmcnt(0)
	v_add_f32_e32 v218, v218, v242
	s_add_u32 s100, s50, 0xc0
	s_addc_u32 s101, s51, 0
	s_and_saveexec_b64 s[40:41], s[98:99]
	global_atomic_add_f32 v251, v218, s[100:101]
	s_or_b64 exec, exec, s[40:41]
	s_waitcnt vmcnt(18)
	v_lshlrev_b32_e32 v242, 16, v186
	v_and_b32_e32 v243, 0xffff0000, v186
	v_lshlrev_b32_e32 v244, 16, v187
	v_and_b32_e32 v245, 0xffff0000, v187
	v_lshlrev_b32_e32 v246, 16, v188
	v_and_b32_e32 v247, 0xffff0000, v188
	v_lshlrev_b32_e32 v248, 16, v189
	v_and_b32_e32 v249, 0xffff0000, v189
	v_pk_fma_f32 v[62:63], v[62:63], v[130:131], v[242:243]
	v_pk_fma_f32 v[64:65], v[64:65], v[132:133], v[244:245]
	v_pk_fma_f32 v[58:59], v[58:59], v[134:135], v[246:247]
	v_pk_fma_f32 v[60:61], v[60:61], v[136:137], v[248:249]
	v_cvt_pk_bf16_f32 v186, v62, v63
	v_cvt_pk_bf16_f32 v187, v64, v65
	v_cvt_pk_bf16_f32 v188, v58, v59
	v_cvt_pk_bf16_f32 v189, v60, v61
	s_add_u32 s6, s94, 0x40000
	s_addc_u32 s7, s95, 0
	global_store_dwordx4 v250, v[186:189], s[6:7] offset:0
	v_pk_mul_f32 v[242:243], v[62:63], v[62:63]
	v_pk_fma_f32 v[242:243], v[64:65], v[64:65], v[242:243]
	v_pk_fma_f32 v[242:243], v[58:59], v[58:59], v[242:243]
	v_pk_fma_f32 v[242:243], v[60:61], v[60:61], v[242:243]
	v_add_f32_e32 v218, v242, v243
	s_waitcnt vmcnt(17)
	v_lshlrev_b32_e32 v242, 16, v190
	v_and_b32_e32 v243, 0xffff0000, v190
	v_lshlrev_b32_e32 v244, 16, v191
	v_and_b32_e32 v245, 0xffff0000, v191
	v_lshlrev_b32_e32 v246, 16, v192
	v_and_b32_e32 v247, 0xffff0000, v192
	v_lshlrev_b32_e32 v248, 16, v193
	v_and_b32_e32 v249, 0xffff0000, v193
	v_pk_fma_f32 v[54:55], v[54:55], v[138:139], v[242:243]
	v_pk_fma_f32 v[56:57], v[56:57], v[140:141], v[244:245]
	v_pk_fma_f32 v[50:51], v[50:51], v[142:143], v[246:247]
	v_pk_fma_f32 v[52:53], v[52:53], v[144:145], v[248:249]
	v_cvt_pk_bf16_f32 v190, v54, v55
	v_cvt_pk_bf16_f32 v191, v56, v57
	v_cvt_pk_bf16_f32 v192, v50, v51
	v_cvt_pk_bf16_f32 v193, v52, v53
	s_add_u32 s6, s94, 0x40000
	s_addc_u32 s7, s95, 0
	global_store_dwordx4 v250, v[190:193], s[6:7] offset:256
	v_pk_mul_f32 v[242:243], v[54:55], v[54:55]
	v_pk_fma_f32 v[242:243], v[56:57], v[56:57], v[242:243]
	v_pk_fma_f32 v[242:243], v[50:51], v[50:51], v[242:243]
	v_pk_fma_f32 v[242:243], v[52:53], v[52:53], v[242:243]
	v_add_f32_e32 v242, v242, v243
	v_add_f32_e32 v218, v218, v242
	ds_bpermute_b32 v242, v219, v218
	s_waitcnt lgkmcnt(0)
	v_add_f32_e32 v218, v218, v242
	ds_bpermute_b32 v242, v241, v218
	s_waitcnt lgkmcnt(0)
	v_add_f32_e32 v218, v218, v242
	s_add_u32 s100, s50, 0x200
	s_addc_u32 s101, s51, 0
	s_and_saveexec_b64 s[40:41], s[98:99]
	global_atomic_add_f32 v251, v218, s[100:101]
	s_or_b64 exec, exec, s[40:41]
	s_waitcnt vmcnt(16)
	v_lshlrev_b32_e32 v242, 16, v194
	v_and_b32_e32 v243, 0xffff0000, v194
	v_lshlrev_b32_e32 v244, 16, v195
	v_and_b32_e32 v245, 0xffff0000, v195
	v_lshlrev_b32_e32 v246, 16, v196
	v_and_b32_e32 v247, 0xffff0000, v196
	v_lshlrev_b32_e32 v248, 16, v197
	v_and_b32_e32 v249, 0xffff0000, v197
	v_pk_fma_f32 v[44:45], v[44:45], v[130:131], v[242:243]
	v_pk_fma_f32 v[46:47], v[46:47], v[132:133], v[244:245]
	v_pk_fma_f32 v[40:41], v[40:41], v[134:135], v[246:247]
	v_pk_fma_f32 v[42:43], v[42:43], v[136:137], v[248:249]
	v_cvt_pk_bf16_f32 v194, v44, v45
	v_cvt_pk_bf16_f32 v195, v46, v47
	v_cvt_pk_bf16_f32 v196, v40, v41
	v_cvt_pk_bf16_f32 v197, v42, v43
	s_add_u32 s6, s94, 0x48000
	s_addc_u32 s7, s95, 0
	global_store_dwordx4 v250, v[194:197], s[6:7] offset:0
	v_pk_mul_f32 v[242:243], v[44:45], v[44:45]
	v_pk_fma_f32 v[242:243], v[46:47], v[46:47], v[242:243]
	v_pk_fma_f32 v[242:243], v[40:41], v[40:41], v[242:243]
	v_pk_fma_f32 v[242:243], v[42:43], v[42:43], v[242:243]
	v_add_f32_e32 v218, v242, v243
	s_waitcnt vmcnt(15)
	v_lshlrev_b32_e32 v242, 16, v198
	v_and_b32_e32 v243, 0xffff0000, v198
	v_lshlrev_b32_e32 v244, 16, v199
	v_and_b32_e32 v245, 0xffff0000, v199
	v_lshlrev_b32_e32 v246, 16, v200
	v_and_b32_e32 v247, 0xffff0000, v200
	v_lshlrev_b32_e32 v248, 16, v201
	v_and_b32_e32 v249, 0xffff0000, v201
	v_pk_fma_f32 v[36:37], v[36:37], v[138:139], v[242:243]
	v_pk_fma_f32 v[38:39], v[38:39], v[140:141], v[244:245]
	v_pk_fma_f32 v[32:33], v[32:33], v[142:143], v[246:247]
	v_pk_fma_f32 v[34:35], v[34:35], v[144:145], v[248:249]
	v_cvt_pk_bf16_f32 v198, v36, v37
	v_cvt_pk_bf16_f32 v199, v38, v39
	v_cvt_pk_bf16_f32 v200, v32, v33
	v_cvt_pk_bf16_f32 v201, v34, v35
	s_add_u32 s6, s94, 0x48000
	s_addc_u32 s7, s95, 0
	global_store_dwordx4 v250, v[198:201], s[6:7] offset:256
	v_pk_mul_f32 v[242:243], v[36:37], v[36:37]
	v_pk_fma_f32 v[242:243], v[38:39], v[38:39], v[242:243]
	v_pk_fma_f32 v[242:243], v[32:33], v[32:33], v[242:243]
	v_pk_fma_f32 v[242:243], v[34:35], v[34:35], v[242:243]
	v_add_f32_e32 v242, v242, v243
	v_add_f32_e32 v218, v218, v242
	ds_bpermute_b32 v242, v219, v218
	s_waitcnt lgkmcnt(0)
	v_add_f32_e32 v218, v218, v242
	ds_bpermute_b32 v242, v241, v218
	s_waitcnt lgkmcnt(0)
	v_add_f32_e32 v218, v218, v242
	s_add_u32 s100, s50, 0x240
	s_addc_u32 s101, s51, 0
	s_and_saveexec_b64 s[40:41], s[98:99]
	global_atomic_add_f32 v251, v218, s[100:101]
	s_or_b64 exec, exec, s[40:41]
	s_waitcnt vmcnt(14)
	v_lshlrev_b32_e32 v242, 16, v146
	v_and_b32_e32 v243, 0xffff0000, v146
	v_lshlrev_b32_e32 v244, 16, v147
	v_and_b32_e32 v245, 0xffff0000, v147
	v_lshlrev_b32_e32 v246, 16, v148
	v_and_b32_e32 v247, 0xffff0000, v148
	v_lshlrev_b32_e32 v248, 16, v149
	v_and_b32_e32 v249, 0xffff0000, v149
	v_pk_fma_f32 v[28:29], v[28:29], v[130:131], v[242:243]
	v_pk_fma_f32 v[30:31], v[30:31], v[132:133], v[244:245]
	v_pk_fma_f32 v[24:25], v[24:25], v[134:135], v[246:247]
	v_pk_fma_f32 v[26:27], v[26:27], v[136:137], v[248:249]
	v_cvt_pk_bf16_f32 v146, v28, v29
	v_cvt_pk_bf16_f32 v147, v30, v31
	v_cvt_pk_bf16_f32 v148, v24, v25
	v_cvt_pk_bf16_f32 v149, v26, v27
	s_add_u32 s6, s94, 0x50000
	s_addc_u32 s7, s95, 0
	global_store_dwordx4 v250, v[146:149], s[6:7] offset:0
	v_pk_mul_f32 v[242:243], v[28:29], v[28:29]
	v_pk_fma_f32 v[242:243], v[30:31], v[30:31], v[242:243]
	v_pk_fma_f32 v[242:243], v[24:25], v[24:25], v[242:243]
	v_pk_fma_f32 v[242:243], v[26:27], v[26:27], v[242:243]
	v_add_f32_e32 v218, v242, v243
	s_waitcnt vmcnt(13)
	v_lshlrev_b32_e32 v242, 16, v150
	v_and_b32_e32 v243, 0xffff0000, v150
	v_lshlrev_b32_e32 v244, 16, v151
	v_and_b32_e32 v245, 0xffff0000, v151
	v_lshlrev_b32_e32 v246, 16, v152
	v_and_b32_e32 v247, 0xffff0000, v152
	v_lshlrev_b32_e32 v248, 16, v153
	v_and_b32_e32 v249, 0xffff0000, v153
	v_pk_fma_f32 v[20:21], v[20:21], v[138:139], v[242:243]
	v_pk_fma_f32 v[22:23], v[22:23], v[140:141], v[244:245]
	v_pk_fma_f32 v[16:17], v[16:17], v[142:143], v[246:247]
	v_pk_fma_f32 v[18:19], v[18:19], v[144:145], v[248:249]
	v_cvt_pk_bf16_f32 v150, v20, v21
	v_cvt_pk_bf16_f32 v151, v22, v23
	v_cvt_pk_bf16_f32 v152, v16, v17
	v_cvt_pk_bf16_f32 v153, v18, v19
	s_add_u32 s6, s94, 0x50000
	s_addc_u32 s7, s95, 0
	global_store_dwordx4 v250, v[150:153], s[6:7] offset:256
	v_pk_mul_f32 v[242:243], v[20:21], v[20:21]
	v_pk_fma_f32 v[242:243], v[22:23], v[22:23], v[242:243]
	v_pk_fma_f32 v[242:243], v[16:17], v[16:17], v[242:243]
	v_pk_fma_f32 v[242:243], v[18:19], v[18:19], v[242:243]
	v_add_f32_e32 v242, v242, v243
	v_add_f32_e32 v218, v218, v242
	ds_bpermute_b32 v242, v219, v218
	s_waitcnt lgkmcnt(0)
	v_add_f32_e32 v218, v218, v242
	ds_bpermute_b32 v242, v241, v218
	s_waitcnt lgkmcnt(0)
	v_add_f32_e32 v218, v218, v242
	s_add_u32 s100, s50, 0x280
	s_addc_u32 s101, s51, 0
	s_and_saveexec_b64 s[40:41], s[98:99]
	global_atomic_add_f32 v251, v218, s[100:101]
	s_or_b64 exec, exec, s[40:41]
	s_waitcnt vmcnt(12)
	v_lshlrev_b32_e32 v242, 16, v154
	v_and_b32_e32 v243, 0xffff0000, v154
	v_lshlrev_b32_e32 v244, 16, v155
	v_and_b32_e32 v245, 0xffff0000, v155
	v_lshlrev_b32_e32 v246, 16, v156
	v_and_b32_e32 v247, 0xffff0000, v156
	v_lshlrev_b32_e32 v248, 16, v157
	v_and_b32_e32 v249, 0xffff0000, v157
	v_pk_fma_f32 v[12:13], v[12:13], v[130:131], v[242:243]
	v_pk_fma_f32 v[14:15], v[14:15], v[132:133], v[244:245]
	v_pk_fma_f32 v[8:9], v[8:9], v[134:135], v[246:247]
	v_pk_fma_f32 v[10:11], v[10:11], v[136:137], v[248:249]
	v_cvt_pk_bf16_f32 v154, v12, v13
	v_cvt_pk_bf16_f32 v155, v14, v15
	v_cvt_pk_bf16_f32 v156, v8, v9
	v_cvt_pk_bf16_f32 v157, v10, v11
	s_add_u32 s6, s94, 0x58000
	s_addc_u32 s7, s95, 0
	global_store_dwordx4 v250, v[154:157], s[6:7] offset:0
	v_pk_mul_f32 v[242:243], v[12:13], v[12:13]
	v_pk_fma_f32 v[242:243], v[14:15], v[14:15], v[242:243]
	v_pk_fma_f32 v[242:243], v[8:9], v[8:9], v[242:243]
	v_pk_fma_f32 v[242:243], v[10:11], v[10:11], v[242:243]
	v_add_f32_e32 v218, v242, v243
	s_waitcnt vmcnt(11)
	v_lshlrev_b32_e32 v242, 16, v210
	v_and_b32_e32 v243, 0xffff0000, v210
	v_lshlrev_b32_e32 v244, 16, v211
	v_and_b32_e32 v245, 0xffff0000, v211
	v_lshlrev_b32_e32 v246, 16, v212
	v_and_b32_e32 v247, 0xffff0000, v212
	v_lshlrev_b32_e32 v248, 16, v213
	v_and_b32_e32 v249, 0xffff0000, v213
	v_pk_fma_f32 v[4:5], v[4:5], v[138:139], v[242:243]
	v_pk_fma_f32 v[6:7], v[6:7], v[140:141], v[244:245]
	v_pk_fma_f32 v[0:1], v[0:1], v[142:143], v[246:247]
	v_pk_fma_f32 v[2:3], v[2:3], v[144:145], v[248:249]
	v_cvt_pk_bf16_f32 v210, v4, v5
	v_cvt_pk_bf16_f32 v211, v6, v7
	v_cvt_pk_bf16_f32 v212, v0, v1
	v_cvt_pk_bf16_f32 v213, v2, v3
	s_add_u32 s6, s94, 0x58000
	s_addc_u32 s7, s95, 0
	global_store_dwordx4 v250, v[210:213], s[6:7] offset:256
	v_pk_mul_f32 v[242:243], v[4:5], v[4:5]
	v_pk_fma_f32 v[242:243], v[6:7], v[6:7], v[242:243]
	v_pk_fma_f32 v[242:243], v[0:1], v[0:1], v[242:243]
	v_pk_fma_f32 v[242:243], v[2:3], v[2:3], v[242:243]
	v_add_f32_e32 v242, v242, v243
	v_add_f32_e32 v218, v218, v242
	ds_bpermute_b32 v242, v219, v218
	s_waitcnt lgkmcnt(0)
	v_add_f32_e32 v218, v218, v242
	ds_bpermute_b32 v242, v241, v218
	s_waitcnt lgkmcnt(0)
	v_add_f32_e32 v218, v218, v242
	s_add_u32 s100, s50, 0x2c0
	s_addc_u32 s101, s51, 0
	s_and_saveexec_b64 s[40:41], s[98:99]
	global_atomic_add_f32 v251, v218, s[100:101]
	s_or_b64 exec, exec, s[40:41]
	s_branch .LBB0_991
